# store widening: attention O epilogue via permlane32_swap to dwordx4; out-proj/MLP-down residual epilogue rewritten by hand (permlane16_swap bf16 dwordx4 stores, 3-row-deep residual load pipeline, batc
# speedup vs baseline: 1.0485x; 1.0208x over previous
.LBB0_95:
	v_div_scale_f32 v35, s[0:1], v34, v34, 1.0
	v_rcp_f32_e32 v36, v35
	v_div_scale_f32 v37, vcc, 1.0, v34, 1.0
	v_mov_b32_e32 v149, v99
	v_fma_f32 v38, -v35, v36, 1.0
	v_fmac_f32_e32 v36, v38, v36
	v_mul_f32_e32 v38, v37, v36
	v_fma_f32 v39, -v35, v38, v37
	v_fmac_f32_e32 v38, v39, v36
	v_fma_f32 v35, -v35, v38, v37
	v_div_fmas_f32 v35, v35, v36, v38
	v_div_fixup_f32 v34, v35, v34, 1.0
	s_waitcnt vmcnt(0) lgkmcnt(0)
	v_pk_mul_f32 v[0:1], v[34:35], v[0:1] op_sel_hi:[0,1]
	v_pk_mul_f32 v[2:3], v[34:35], v[2:3] op_sel_hi:[0,1]
	v_pk_mul_f32 v[4:5], v[34:35], v[4:5] op_sel_hi:[0,1]
	v_pk_mul_f32 v[6:7], v[34:35], v[6:7] op_sel_hi:[0,1]
	v_pk_mul_f32 v[8:9], v[34:35], v[8:9] op_sel_hi:[0,1]
	v_pk_mul_f32 v[10:11], v[34:35], v[10:11] op_sel_hi:[0,1]
	v_pk_mul_f32 v[12:13], v[34:35], v[12:13] op_sel_hi:[0,1]
	v_pk_mul_f32 v[14:15], v[34:35], v[14:15] op_sel_hi:[0,1]
	v_pk_mul_f32 v[16:17], v[34:35], v[16:17] op_sel_hi:[0,1]
	v_pk_mul_f32 v[18:19], v[34:35], v[18:19] op_sel_hi:[0,1]
	v_pk_mul_f32 v[20:21], v[34:35], v[20:21] op_sel_hi:[0,1]
	v_pk_mul_f32 v[22:23], v[34:35], v[22:23] op_sel_hi:[0,1]
	v_pk_mul_f32 v[24:25], v[34:35], v[24:25] op_sel_hi:[0,1]
	v_pk_mul_f32 v[26:27], v[34:35], v[26:27] op_sel_hi:[0,1]
	v_pk_mul_f32 v[28:29], v[34:35], v[28:29] op_sel_hi:[0,1]
	v_pk_mul_f32 v[30:31], v[34:35], v[30:31] op_sel_hi:[0,1]
	v_lshl_add_u64 v[32:33], v[148:149], 1, v[32:33]
	v_lshl_add_u64 v[32:33], v[148:149], 1, v[32:33]
	v_cvt_pk_bf16_f32 v16, v16, v17
	v_cvt_pk_bf16_f32 v17, v18, v19
	v_cvt_pk_bf16_f32 v18, v20, v21
	v_cvt_pk_bf16_f32 v19, v22, v23
	v_cvt_pk_bf16_f32 v20, v24, v25
	v_cvt_pk_bf16_f32 v21, v26, v27
	v_cvt_pk_bf16_f32 v22, v28, v29
	v_cvt_pk_bf16_f32 v23, v30, v31
	v_cvt_pk_bf16_f32 v0, v0, v1
	v_cvt_pk_bf16_f32 v1, v2, v3
	v_cvt_pk_bf16_f32 v2, v4, v5
	v_cvt_pk_bf16_f32 v3, v6, v7
	v_cvt_pk_bf16_f32 v4, v8, v9
	v_cvt_pk_bf16_f32 v5, v10, v11
	v_cvt_pk_bf16_f32 v6, v12, v13
	v_cvt_pk_bf16_f32 v7, v14, v15
	s_add_i32 s14, s14, s3
	s_add_i32 s13, s13, s3
	s_nop 1
	v_permlane32_swap_b32 v16, v18
	v_permlane32_swap_b32 v17, v19
	v_permlane32_swap_b32 v20, v22
	v_permlane32_swap_b32 v21, v23
	v_permlane32_swap_b32 v0, v2
	v_permlane32_swap_b32 v1, v3
	v_permlane32_swap_b32 v4, v6
	v_permlane32_swap_b32 v5, v7
	s_cmp_ge_i32 s14, s21
	global_store_dwordx4 v[32:33], v[16:19], off
	global_store_dwordx4 v[32:33], v[20:23], off offset:32
	global_store_dwordx4 v[32:33], v[0:3], off offset:64
	global_store_dwordx4 v[32:33], v[4:7], off offset:96
	s_cbranch_scc1 .LBB0_599

.LBB0_874:
	s_cmpk_gt_i32 s56, 0x7f
	s_cbranch_scc1 .Lresid_orig
	s_and_b64 vcc, exec, s[10:11]
	s_cbranch_vccz .Lresid_orig
	v_readlane_b32 s62, v252, 7
	v_readlane_b32 s63, v252, 8
	s_lshr_b32 s20, s56, 4
	s_mul_i32 s20, s20, 0x6000
	s_add_u32 s44, s66, s20
	s_addc_u32 s45, s12, 0
	s_add_u32 s46, s13, s20
	s_addc_u32 s47, s26, 0
	s_mov_b32 s60, s38
	s_mov_b32 s61, s95
	v_lshl_or_b32 v236, s57, 8, v246
	v_lshl_add_u32 v237, s56, 8, v244
	v_lshlrev_b32_e32 v210, 2, v236
	v_lshl_add_u32 v211, v237, 12, v210
	v_and_b32_e32 v212, 4, v246
	v_mul_u32_u24_e32 v212, 6, v212
	v_lshl_add_u32 v212, v236, 1, v212
	v_lshl_add_u32 v212, v237, 11, v212
	v_lshlrev_b32_e32 v213, 2, v237
	v_lshlrev_b32_e32 v214, 2, v231
	v_lshlrev_b32_e32 v215, 2, v232
	global_load_dwordx4 v[60:63], v210, s[44:45] offset:0
	global_load_dwordx4 v[64:67], v210, s[44:45] offset:64
	global_load_dwordx4 v[68:71], v210, s[44:45] offset:512
	global_load_dwordx4 v[72:75], v210, s[44:45] offset:576
	global_load_dwordx4 v[148:151], v210, s[46:47] offset:0
	global_load_dwordx4 v[152:155], v210, s[46:47] offset:64
	global_load_dwordx4 v[156:159], v210, s[46:47] offset:512
	global_load_dwordx4 v[160:163], v210, s[46:47] offset:576
	global_load_dwordx4 v[194:197], v210, s[8:9] offset:0
	global_load_dwordx4 v[198:201], v210, s[8:9] offset:64
	global_load_dwordx4 v[202:205], v210, s[8:9] offset:512
	global_load_dwordx4 v[206:209], v210, s[8:9] offset:576
	s_mov_b32 s72, s60
	s_mov_b32 s73, s61
	global_load_dwordx4 v[164:167], v211, s[72:73] offset:0
	global_load_dwordx4 v[168:171], v211, s[72:73] offset:64
	global_load_dwordx4 v[172:175], v211, s[72:73] offset:512
	global_load_dwordx4 v[176:179], v211, s[72:73] offset:576
	s_waitcnt vmcnt(4)
	v_pk_add_f32 v[148:149], v[148:149], 1.0 op_sel_hi:[1,0]
	v_pk_add_f32 v[150:151], v[150:151], 1.0 op_sel_hi:[1,0]
	v_pk_mul_f32 v[148:149], v[194:195], v[148:149]
	v_pk_mul_f32 v[150:151], v[196:197], v[150:151]
	v_pk_add_f32 v[152:153], v[152:153], 1.0 op_sel_hi:[1,0]
	v_pk_add_f32 v[154:155], v[154:155], 1.0 op_sel_hi:[1,0]
	v_pk_mul_f32 v[152:153], v[198:199], v[152:153]
	v_pk_mul_f32 v[154:155], v[200:201], v[154:155]
	v_pk_add_f32 v[156:157], v[156:157], 1.0 op_sel_hi:[1,0]
	v_pk_add_f32 v[158:159], v[158:159], 1.0 op_sel_hi:[1,0]
	v_pk_mul_f32 v[156:157], v[202:203], v[156:157]
	v_pk_mul_f32 v[158:159], v[204:205], v[158:159]
	v_pk_add_f32 v[160:161], v[160:161], 1.0 op_sel_hi:[1,0]
	v_pk_add_f32 v[162:163], v[162:163], 1.0 op_sel_hi:[1,0]
	v_pk_mul_f32 v[160:161], v[206:207], v[160:161]
	v_pk_mul_f32 v[162:163], v[208:209], v[162:163]
	s_add_u32 s72, s60, 0x10000
	s_addc_u32 s73, s61, 0
	global_load_dwordx4 v[194:197], v211, s[72:73] offset:0
	global_load_dwordx4 v[198:201], v211, s[72:73] offset:64
	global_load_dwordx4 v[202:205], v211, s[72:73] offset:512
	global_load_dwordx4 v[206:209], v211, s[72:73] offset:576
	v_mov_b32_e32 v216, 0
	v_mov_b32_e32 v217, 0
	v_mov_b32_e32 v218, 0
	v_mov_b32_e32 v219, 0
	v_mov_b32_e32 v228, 0
	v_mov_b32_e32 v229, 0
	v_mov_b32_e32 v234, 0
	v_mov_b32_e32 v235, 0
	s_waitcnt vmcnt(4)
	s_mov_b32 s74, s62
	s_mov_b32 s75, s63
	s_mov_b32 s76, s88
	s_mov_b32 s77, s89
	v_pk_fma_f32 v[164:165], v[144:145], v[60:61], v[164:165]
	v_pk_fma_f32 v[166:167], v[146:147], v[62:63], v[166:167]
	global_store_dwordx4 v211, v[164:167], s[74:75] offset:0
	v_fmac_f32_e32 v216, v164, v164
	v_fmac_f32_e32 v216, v165, v165
	v_fmac_f32_e32 v216, v166, v166
	v_fmac_f32_e32 v216, v167, v167
	v_pk_mul_f32 v[144:145], v[148:149], v[164:165]
	v_pk_mul_f32 v[146:147], v[150:151], v[166:167]
	v_pk_fma_f32 v[168:169], v[140:141], v[64:65], v[168:169]
	v_pk_fma_f32 v[170:171], v[142:143], v[66:67], v[170:171]
	global_store_dwordx4 v211, v[168:171], s[74:75] offset:64
	v_fmac_f32_e32 v216, v168, v168
	v_fmac_f32_e32 v216, v169, v169
	v_fmac_f32_e32 v216, v170, v170
	v_fmac_f32_e32 v216, v171, v171
	v_pk_mul_f32 v[140:141], v[152:153], v[168:169]
	v_pk_mul_f32 v[142:143], v[154:155], v[170:171]
	v_cvt_pk_bf16_f32 v144, v144, v145
	v_cvt_pk_bf16_f32 v145, v146, v147
	v_cvt_pk_bf16_f32 v146, v140, v141
	v_cvt_pk_bf16_f32 v147, v142, v143
	s_nop 1
	v_permlane16_swap_b32 v144, v146
	v_permlane16_swap_b32 v145, v147
	global_store_dwordx4 v212, v[144:147], s[76:77] offset:0
	v_pk_fma_f32 v[172:173], v[136:137], v[68:69], v[172:173]
	v_pk_fma_f32 v[174:175], v[138:139], v[70:71], v[174:175]
	global_store_dwordx4 v211, v[172:175], s[74:75] offset:512
	v_fmac_f32_e32 v216, v172, v172
	v_fmac_f32_e32 v216, v173, v173
	v_fmac_f32_e32 v216, v174, v174
	v_fmac_f32_e32 v216, v175, v175
	v_pk_mul_f32 v[136:137], v[156:157], v[172:173]
	v_pk_mul_f32 v[138:139], v[158:159], v[174:175]
	v_pk_fma_f32 v[176:177], v[132:133], v[72:73], v[176:177]
	v_pk_fma_f32 v[178:179], v[134:135], v[74:75], v[178:179]
	global_store_dwordx4 v211, v[176:179], s[74:75] offset:576
	v_fmac_f32_e32 v216, v176, v176
	v_fmac_f32_e32 v216, v177, v177
	v_fmac_f32_e32 v216, v178, v178
	v_fmac_f32_e32 v216, v179, v179
	v_pk_mul_f32 v[132:133], v[160:161], v[176:177]
	v_pk_mul_f32 v[134:135], v[162:163], v[178:179]
	v_cvt_pk_bf16_f32 v136, v136, v137
	v_cvt_pk_bf16_f32 v137, v138, v139
	v_cvt_pk_bf16_f32 v138, v132, v133
	v_cvt_pk_bf16_f32 v139, v134, v135
	s_nop 1
	v_permlane16_swap_b32 v136, v138
	v_permlane16_swap_b32 v137, v139
	global_store_dwordx4 v212, v[136:139], s[76:77] offset:256
	s_add_u32 s72, s60, 0x20000
	s_addc_u32 s73, s61, 0
	global_load_dwordx4 v[164:167], v211, s[72:73] offset:0
	global_load_dwordx4 v[168:171], v211, s[72:73] offset:64
	global_load_dwordx4 v[172:175], v211, s[72:73] offset:512
	global_load_dwordx4 v[176:179], v211, s[72:73] offset:576
	s_add_u32 s72, s60, 0x30000
	s_addc_u32 s73, s61, 0
	global_load_dwordx4 v[144:147], v211, s[72:73] offset:0
	global_load_dwordx4 v[140:143], v211, s[72:73] offset:64
	global_load_dwordx4 v[136:139], v211, s[72:73] offset:512
	global_load_dwordx4 v[132:135], v211, s[72:73] offset:576
	s_waitcnt vmcnt(14)
	s_add_u32 s74, s62, 0x10000
	s_addc_u32 s75, s63, 0
	s_add_u32 s76, s88, 0x8000
	s_addc_u32 s77, s89, 0
	v_pk_fma_f32 v[194:195], v[128:129], v[60:61], v[194:195]
	v_pk_fma_f32 v[196:197], v[130:131], v[62:63], v[196:197]
	global_store_dwordx4 v211, v[194:197], s[74:75] offset:0
	v_fmac_f32_e32 v217, v194, v194
	v_fmac_f32_e32 v217, v195, v195
	v_fmac_f32_e32 v217, v196, v196
	v_fmac_f32_e32 v217, v197, v197
	v_pk_mul_f32 v[128:129], v[148:149], v[194:195]
	v_pk_mul_f32 v[130:131], v[150:151], v[196:197]
	v_pk_fma_f32 v[198:199], v[124:125], v[64:65], v[198:199]
	v_pk_fma_f32 v[200:201], v[126:127], v[66:67], v[200:201]
	global_store_dwordx4 v211, v[198:201], s[74:75] offset:64
	v_fmac_f32_e32 v217, v198, v198
	v_fmac_f32_e32 v217, v199, v199
	v_fmac_f32_e32 v217, v200, v200
	v_fmac_f32_e32 v217, v201, v201
	v_pk_mul_f32 v[124:125], v[152:153], v[198:199]
	v_pk_mul_f32 v[126:127], v[154:155], v[200:201]
	v_cvt_pk_bf16_f32 v128, v128, v129
	v_cvt_pk_bf16_f32 v129, v130, v131
	v_cvt_pk_bf16_f32 v130, v124, v125
	v_cvt_pk_bf16_f32 v131, v126, v127
	s_nop 1
	v_permlane16_swap_b32 v128, v130
	v_permlane16_swap_b32 v129, v131
	global_store_dwordx4 v212, v[128:131], s[76:77] offset:0
	v_pk_fma_f32 v[202:203], v[120:121], v[68:69], v[202:203]
	v_pk_fma_f32 v[204:205], v[122:123], v[70:71], v[204:205]
	global_store_dwordx4 v211, v[202:205], s[74:75] offset:512
	v_fmac_f32_e32 v217, v202, v202
	v_fmac_f32_e32 v217, v203, v203
	v_fmac_f32_e32 v217, v204, v204
	v_fmac_f32_e32 v217, v205, v205
	v_pk_mul_f32 v[120:121], v[156:157], v[202:203]
	v_pk_mul_f32 v[122:123], v[158:159], v[204:205]
	v_pk_fma_f32 v[206:207], v[116:117], v[72:73], v[206:207]
	v_pk_fma_f32 v[208:209], v[118:119], v[74:75], v[208:209]
	global_store_dwordx4 v211, v[206:209], s[74:75] offset:576
	v_fmac_f32_e32 v217, v206, v206
	v_fmac_f32_e32 v217, v207, v207
	v_fmac_f32_e32 v217, v208, v208
	v_fmac_f32_e32 v217, v209, v209
	v_pk_mul_f32 v[116:117], v[160:161], v[206:207]
	v_pk_mul_f32 v[118:119], v[162:163], v[208:209]
	v_cvt_pk_bf16_f32 v120, v120, v121
	v_cvt_pk_bf16_f32 v121, v122, v123
	v_cvt_pk_bf16_f32 v122, v116, v117
	v_cvt_pk_bf16_f32 v123, v118, v119
	s_nop 1
	v_permlane16_swap_b32 v120, v122
	v_permlane16_swap_b32 v121, v123
	global_store_dwordx4 v212, v[120:123], s[76:77] offset:256
	s_add_u32 s72, s60, 0x80000
	s_addc_u32 s73, s61, 0
	global_load_dwordx4 v[194:197], v211, s[72:73] offset:0
	global_load_dwordx4 v[198:201], v211, s[72:73] offset:64
	global_load_dwordx4 v[202:205], v211, s[72:73] offset:512
	global_load_dwordx4 v[206:209], v211, s[72:73] offset:576
	s_add_u32 s72, s60, 0x90000
	s_addc_u32 s73, s61, 0
	global_load_dwordx4 v[128:131], v211, s[72:73] offset:0
	global_load_dwordx4 v[124:127], v211, s[72:73] offset:64
	global_load_dwordx4 v[120:123], v211, s[72:73] offset:512
	global_load_dwordx4 v[116:119], v211, s[72:73] offset:576
	s_waitcnt vmcnt(18)
	s_add_u32 s74, s62, 0x20000
	s_addc_u32 s75, s63, 0
	s_add_u32 s76, s88, 0x10000
	s_addc_u32 s77, s89, 0
	v_pk_fma_f32 v[164:165], v[112:113], v[60:61], v[164:165]
	v_pk_fma_f32 v[166:167], v[114:115], v[62:63], v[166:167]
	global_store_dwordx4 v211, v[164:167], s[74:75] offset:0
	v_fmac_f32_e32 v218, v164, v164
	v_fmac_f32_e32 v218, v165, v165
	v_fmac_f32_e32 v218, v166, v166
	v_fmac_f32_e32 v218, v167, v167
	v_pk_mul_f32 v[112:113], v[148:149], v[164:165]
	v_pk_mul_f32 v[114:115], v[150:151], v[166:167]
	v_pk_fma_f32 v[168:169], v[108:109], v[64:65], v[168:169]
	v_pk_fma_f32 v[170:171], v[110:111], v[66:67], v[170:171]
	global_store_dwordx4 v211, v[168:171], s[74:75] offset:64
	v_fmac_f32_e32 v218, v168, v168
	v_fmac_f32_e32 v218, v169, v169
	v_fmac_f32_e32 v218, v170, v170
	v_fmac_f32_e32 v218, v171, v171
	v_pk_mul_f32 v[108:109], v[152:153], v[168:169]
	v_pk_mul_f32 v[110:111], v[154:155], v[170:171]
	v_cvt_pk_bf16_f32 v112, v112, v113
	v_cvt_pk_bf16_f32 v113, v114, v115
	v_cvt_pk_bf16_f32 v114, v108, v109
	v_cvt_pk_bf16_f32 v115, v110, v111
	s_nop 1
	v_permlane16_swap_b32 v112, v114
	v_permlane16_swap_b32 v113, v115
	global_store_dwordx4 v212, v[112:115], s[76:77] offset:0
	v_pk_fma_f32 v[172:173], v[104:105], v[68:69], v[172:173]
	v_pk_fma_f32 v[174:175], v[106:107], v[70:71], v[174:175]
	global_store_dwordx4 v211, v[172:175], s[74:75] offset:512
	v_fmac_f32_e32 v218, v172, v172
	v_fmac_f32_e32 v218, v173, v173
	v_fmac_f32_e32 v218, v174, v174
	v_fmac_f32_e32 v218, v175, v175
	v_pk_mul_f32 v[104:105], v[156:157], v[172:173]
	v_pk_mul_f32 v[106:107], v[158:159], v[174:175]
	v_pk_fma_f32 v[176:177], v[100:101], v[72:73], v[176:177]
	v_pk_fma_f32 v[178:179], v[102:103], v[74:75], v[178:179]
	global_store_dwordx4 v211, v[176:179], s[74:75] offset:576
	v_fmac_f32_e32 v218, v176, v176
	v_fmac_f32_e32 v218, v177, v177
	v_fmac_f32_e32 v218, v178, v178
	v_fmac_f32_e32 v218, v179, v179
	v_pk_mul_f32 v[100:101], v[160:161], v[176:177]
	v_pk_mul_f32 v[102:103], v[162:163], v[178:179]
	v_cvt_pk_bf16_f32 v104, v104, v105
	v_cvt_pk_bf16_f32 v105, v106, v107
	v_cvt_pk_bf16_f32 v106, v100, v101
	v_cvt_pk_bf16_f32 v107, v102, v103
	s_nop 1
	v_permlane16_swap_b32 v104, v106
	v_permlane16_swap_b32 v105, v107
	global_store_dwordx4 v212, v[104:107], s[76:77] offset:256
	s_add_u32 s72, s60, 0xa0000
	s_addc_u32 s73, s61, 0
	global_load_dwordx4 v[164:167], v211, s[72:73] offset:0
	global_load_dwordx4 v[168:171], v211, s[72:73] offset:64
	global_load_dwordx4 v[172:175], v211, s[72:73] offset:512
	global_load_dwordx4 v[176:179], v211, s[72:73] offset:576
	s_add_u32 s72, s60, 0xb0000
	s_addc_u32 s73, s61, 0
	global_load_dwordx4 v[112:115], v211, s[72:73] offset:0
	global_load_dwordx4 v[108:111], v211, s[72:73] offset:64
	global_load_dwordx4 v[104:107], v211, s[72:73] offset:512
	global_load_dwordx4 v[100:103], v211, s[72:73] offset:576
	s_waitcnt vmcnt(28)
	s_add_u32 s74, s62, 0x30000
	s_addc_u32 s75, s63, 0
	s_add_u32 s76, s88, 0x18000
	s_addc_u32 s77, s89, 0
	v_pk_fma_f32 v[144:145], v[92:93], v[60:61], v[144:145]
	v_pk_fma_f32 v[146:147], v[94:95], v[62:63], v[146:147]
	global_store_dwordx4 v211, v[144:147], s[74:75] offset:0
	v_fmac_f32_e32 v219, v144, v144
	v_fmac_f32_e32 v219, v145, v145
	v_fmac_f32_e32 v219, v146, v146
	v_fmac_f32_e32 v219, v147, v147
	v_pk_mul_f32 v[92:93], v[148:149], v[144:145]
	v_pk_mul_f32 v[94:95], v[150:151], v[146:147]
	v_pk_fma_f32 v[140:141], v[88:89], v[64:65], v[140:141]
	v_pk_fma_f32 v[142:143], v[90:91], v[66:67], v[142:143]
	global_store_dwordx4 v211, v[140:143], s[74:75] offset:64
	v_fmac_f32_e32 v219, v140, v140
	v_fmac_f32_e32 v219, v141, v141
	v_fmac_f32_e32 v219, v142, v142
	v_fmac_f32_e32 v219, v143, v143
	v_pk_mul_f32 v[88:89], v[152:153], v[140:141]
	v_pk_mul_f32 v[90:91], v[154:155], v[142:143]
	v_cvt_pk_bf16_f32 v92, v92, v93
	v_cvt_pk_bf16_f32 v93, v94, v95
	v_cvt_pk_bf16_f32 v94, v88, v89
	v_cvt_pk_bf16_f32 v95, v90, v91
	s_nop 1
	v_permlane16_swap_b32 v92, v94
	v_permlane16_swap_b32 v93, v95
	global_store_dwordx4 v212, v[92:95], s[76:77] offset:0
	v_pk_fma_f32 v[136:137], v[84:85], v[68:69], v[136:137]
	v_pk_fma_f32 v[138:139], v[86:87], v[70:71], v[138:139]
	global_store_dwordx4 v211, v[136:139], s[74:75] offset:512
	v_fmac_f32_e32 v219, v136, v136
	v_fmac_f32_e32 v219, v137, v137
	v_fmac_f32_e32 v219, v138, v138
	v_fmac_f32_e32 v219, v139, v139
	v_pk_mul_f32 v[84:85], v[156:157], v[136:137]
	v_pk_mul_f32 v[86:87], v[158:159], v[138:139]
	v_pk_fma_f32 v[132:133], v[80:81], v[72:73], v[132:133]
	v_pk_fma_f32 v[134:135], v[82:83], v[74:75], v[134:135]
	global_store_dwordx4 v211, v[132:135], s[74:75] offset:576
	v_fmac_f32_e32 v219, v132, v132
	v_fmac_f32_e32 v219, v133, v133
	v_fmac_f32_e32 v219, v134, v134
	v_fmac_f32_e32 v219, v135, v135
	v_pk_mul_f32 v[80:81], v[160:161], v[132:133]
	v_pk_mul_f32 v[82:83], v[162:163], v[134:135]
	v_cvt_pk_bf16_f32 v84, v84, v85
	v_cvt_pk_bf16_f32 v85, v86, v87
	v_cvt_pk_bf16_f32 v86, v80, v81
	v_cvt_pk_bf16_f32 v87, v82, v83
	s_nop 1
	v_permlane16_swap_b32 v84, v86
	v_permlane16_swap_b32 v85, v87
	global_store_dwordx4 v212, v[84:87], s[76:77] offset:256
	s_waitcnt vmcnt(24)
	s_add_u32 s74, s62, 0x80000
	s_addc_u32 s75, s63, 0
	s_add_u32 s76, s88, 0x40000
	s_addc_u32 s77, s89, 0
	v_pk_fma_f32 v[194:195], v[76:77], v[60:61], v[194:195]
	v_pk_fma_f32 v[196:197], v[78:79], v[62:63], v[196:197]
	global_store_dwordx4 v211, v[194:197], s[74:75] offset:0
	v_fmac_f32_e32 v228, v194, v194
	v_fmac_f32_e32 v228, v195, v195
	v_fmac_f32_e32 v228, v196, v196
	v_fmac_f32_e32 v228, v197, v197
	v_pk_mul_f32 v[76:77], v[148:149], v[194:195]
	v_pk_mul_f32 v[78:79], v[150:151], v[196:197]
	v_pk_fma_f32 v[198:199], v[56:57], v[64:65], v[198:199]
	v_pk_fma_f32 v[200:201], v[58:59], v[66:67], v[200:201]
	global_store_dwordx4 v211, v[198:201], s[74:75] offset:64
	v_fmac_f32_e32 v228, v198, v198
	v_fmac_f32_e32 v228, v199, v199
	v_fmac_f32_e32 v228, v200, v200
	v_fmac_f32_e32 v228, v201, v201
	v_pk_mul_f32 v[56:57], v[152:153], v[198:199]
	v_pk_mul_f32 v[58:59], v[154:155], v[200:201]
	v_cvt_pk_bf16_f32 v76, v76, v77
	v_cvt_pk_bf16_f32 v77, v78, v79
	v_cvt_pk_bf16_f32 v78, v56, v57
	v_cvt_pk_bf16_f32 v79, v58, v59
	s_nop 1
	v_permlane16_swap_b32 v76, v78
	v_permlane16_swap_b32 v77, v79
	global_store_dwordx4 v212, v[76:79], s[76:77] offset:0
	v_pk_fma_f32 v[202:203], v[52:53], v[68:69], v[202:203]
	v_pk_fma_f32 v[204:205], v[54:55], v[70:71], v[204:205]
	global_store_dwordx4 v211, v[202:205], s[74:75] offset:512
	v_fmac_f32_e32 v228, v202, v202
	v_fmac_f32_e32 v228, v203, v203
	v_fmac_f32_e32 v228, v204, v204
	v_fmac_f32_e32 v228, v205, v205
	v_pk_mul_f32 v[52:53], v[156:157], v[202:203]
	v_pk_mul_f32 v[54:55], v[158:159], v[204:205]
	v_pk_fma_f32 v[206:207], v[48:49], v[72:73], v[206:207]
	v_pk_fma_f32 v[208:209], v[50:51], v[74:75], v[208:209]
	global_store_dwordx4 v211, v[206:209], s[74:75] offset:576
	v_fmac_f32_e32 v228, v206, v206
	v_fmac_f32_e32 v228, v207, v207
	v_fmac_f32_e32 v228, v208, v208
	v_fmac_f32_e32 v228, v209, v209
	v_pk_mul_f32 v[48:49], v[160:161], v[206:207]
	v_pk_mul_f32 v[50:51], v[162:163], v[208:209]
	v_cvt_pk_bf16_f32 v52, v52, v53
	v_cvt_pk_bf16_f32 v53, v54, v55
	v_cvt_pk_bf16_f32 v54, v48, v49
	v_cvt_pk_bf16_f32 v55, v50, v51
	s_nop 1
	v_permlane16_swap_b32 v52, v54
	v_permlane16_swap_b32 v53, v55
	global_store_dwordx4 v212, v[52:55], s[76:77] offset:256
	s_waitcnt vmcnt(26)
	s_add_u32 s74, s62, 0x90000
	s_addc_u32 s75, s63, 0
	s_add_u32 s76, s88, 0x48000
	s_addc_u32 s77, s89, 0
	v_pk_fma_f32 v[128:129], v[44:45], v[60:61], v[128:129]
	v_pk_fma_f32 v[130:131], v[46:47], v[62:63], v[130:131]
	global_store_dwordx4 v211, v[128:131], s[74:75] offset:0
	v_fmac_f32_e32 v229, v128, v128
	v_fmac_f32_e32 v229, v129, v129
	v_fmac_f32_e32 v229, v130, v130
	v_fmac_f32_e32 v229, v131, v131
	v_pk_mul_f32 v[44:45], v[148:149], v[128:129]
	v_pk_mul_f32 v[46:47], v[150:151], v[130:131]
	v_pk_fma_f32 v[124:125], v[40:41], v[64:65], v[124:125]
	v_pk_fma_f32 v[126:127], v[42:43], v[66:67], v[126:127]
	global_store_dwordx4 v211, v[124:127], s[74:75] offset:64
	v_fmac_f32_e32 v229, v124, v124
	v_fmac_f32_e32 v229, v125, v125
	v_fmac_f32_e32 v229, v126, v126
	v_fmac_f32_e32 v229, v127, v127
	v_pk_mul_f32 v[40:41], v[152:153], v[124:125]
	v_pk_mul_f32 v[42:43], v[154:155], v[126:127]
	v_cvt_pk_bf16_f32 v44, v44, v45
	v_cvt_pk_bf16_f32 v45, v46, v47
	v_cvt_pk_bf16_f32 v46, v40, v41
	v_cvt_pk_bf16_f32 v47, v42, v43
	s_nop 1
	v_permlane16_swap_b32 v44, v46
	v_permlane16_swap_b32 v45, v47
	global_store_dwordx4 v212, v[44:47], s[76:77] offset:0
	v_pk_fma_f32 v[120:121], v[36:37], v[68:69], v[120:121]
	v_pk_fma_f32 v[122:123], v[38:39], v[70:71], v[122:123]
	global_store_dwordx4 v211, v[120:123], s[74:75] offset:512
	v_fmac_f32_e32 v229, v120, v120
	v_fmac_f32_e32 v229, v121, v121
	v_fmac_f32_e32 v229, v122, v122
	v_fmac_f32_e32 v229, v123, v123
	v_pk_mul_f32 v[36:37], v[156:157], v[120:121]
	v_pk_mul_f32 v[38:39], v[158:159], v[122:123]
	v_pk_fma_f32 v[116:117], v[32:33], v[72:73], v[116:117]
	v_pk_fma_f32 v[118:119], v[34:35], v[74:75], v[118:119]
	global_store_dwordx4 v211, v[116:119], s[74:75] offset:576
	v_fmac_f32_e32 v229, v116, v116
	v_fmac_f32_e32 v229, v117, v117
	v_fmac_f32_e32 v229, v118, v118
	v_fmac_f32_e32 v229, v119, v119
	v_pk_mul_f32 v[32:33], v[160:161], v[116:117]
	v_pk_mul_f32 v[34:35], v[162:163], v[118:119]
	v_cvt_pk_bf16_f32 v36, v36, v37
	v_cvt_pk_bf16_f32 v37, v38, v39
	v_cvt_pk_bf16_f32 v38, v32, v33
	v_cvt_pk_bf16_f32 v39, v34, v35
	s_nop 1
	v_permlane16_swap_b32 v36, v38
	v_permlane16_swap_b32 v37, v39
	global_store_dwordx4 v212, v[36:39], s[76:77] offset:256
	s_waitcnt vmcnt(22)
	s_add_u32 s74, s62, 0xa0000
	s_addc_u32 s75, s63, 0
	s_add_u32 s76, s88, 0x50000
	s_addc_u32 s77, s89, 0
	v_pk_fma_f32 v[164:165], v[28:29], v[60:61], v[164:165]
	v_pk_fma_f32 v[166:167], v[30:31], v[62:63], v[166:167]
	global_store_dwordx4 v211, v[164:167], s[74:75] offset:0
	v_fmac_f32_e32 v234, v164, v164
	v_fmac_f32_e32 v234, v165, v165
	v_fmac_f32_e32 v234, v166, v166
	v_fmac_f32_e32 v234, v167, v167
	v_pk_mul_f32 v[28:29], v[148:149], v[164:165]
	v_pk_mul_f32 v[30:31], v[150:151], v[166:167]
	v_pk_fma_f32 v[168:169], v[24:25], v[64:65], v[168:169]
	v_pk_fma_f32 v[170:171], v[26:27], v[66:67], v[170:171]
	global_store_dwordx4 v211, v[168:171], s[74:75] offset:64
	v_fmac_f32_e32 v234, v168, v168
	v_fmac_f32_e32 v234, v169, v169
	v_fmac_f32_e32 v234, v170, v170
	v_fmac_f32_e32 v234, v171, v171
	v_pk_mul_f32 v[24:25], v[152:153], v[168:169]
	v_pk_mul_f32 v[26:27], v[154:155], v[170:171]
	v_cvt_pk_bf16_f32 v28, v28, v29
	v_cvt_pk_bf16_f32 v29, v30, v31
	v_cvt_pk_bf16_f32 v30, v24, v25
	v_cvt_pk_bf16_f32 v31, v26, v27
	s_nop 1
	v_permlane16_swap_b32 v28, v30
	v_permlane16_swap_b32 v29, v31
	global_store_dwordx4 v212, v[28:31], s[76:77] offset:0
	v_pk_fma_f32 v[172:173], v[20:21], v[68:69], v[172:173]
	v_pk_fma_f32 v[174:175], v[22:23], v[70:71], v[174:175]
	global_store_dwordx4 v211, v[172:175], s[74:75] offset:512
	v_fmac_f32_e32 v234, v172, v172
	v_fmac_f32_e32 v234, v173, v173
	v_fmac_f32_e32 v234, v174, v174
	v_fmac_f32_e32 v234, v175, v175
	v_pk_mul_f32 v[20:21], v[156:157], v[172:173]
	v_pk_mul_f32 v[22:23], v[158:159], v[174:175]
	v_pk_fma_f32 v[176:177], v[16:17], v[72:73], v[176:177]
	v_pk_fma_f32 v[178:179], v[18:19], v[74:75], v[178:179]
	global_store_dwordx4 v211, v[176:179], s[74:75] offset:576
	v_fmac_f32_e32 v234, v176, v176
	v_fmac_f32_e32 v234, v177, v177
	v_fmac_f32_e32 v234, v178, v178
	v_fmac_f32_e32 v234, v179, v179
	v_pk_mul_f32 v[16:17], v[160:161], v[176:177]
	v_pk_mul_f32 v[18:19], v[162:163], v[178:179]
	v_cvt_pk_bf16_f32 v20, v20, v21
	v_cvt_pk_bf16_f32 v21, v22, v23
	v_cvt_pk_bf16_f32 v22, v16, v17
	v_cvt_pk_bf16_f32 v23, v18, v19
	s_nop 1
	v_permlane16_swap_b32 v20, v22
	v_permlane16_swap_b32 v21, v23
	global_store_dwordx4 v212, v[20:23], s[76:77] offset:256
	s_waitcnt vmcnt(24)
	s_add_u32 s74, s62, 0xb0000
	s_addc_u32 s75, s63, 0
	s_add_u32 s76, s88, 0x58000
	s_addc_u32 s77, s89, 0
	v_pk_fma_f32 v[112:113], v[12:13], v[60:61], v[112:113]
	v_pk_fma_f32 v[114:115], v[14:15], v[62:63], v[114:115]
	global_store_dwordx4 v211, v[112:115], s[74:75] offset:0
	v_fmac_f32_e32 v235, v112, v112
	v_fmac_f32_e32 v235, v113, v113
	v_fmac_f32_e32 v235, v114, v114
	v_fmac_f32_e32 v235, v115, v115
	v_pk_mul_f32 v[12:13], v[148:149], v[112:113]
	v_pk_mul_f32 v[14:15], v[150:151], v[114:115]
	v_pk_fma_f32 v[108:109], v[8:9], v[64:65], v[108:109]
	v_pk_fma_f32 v[110:111], v[10:11], v[66:67], v[110:111]
	global_store_dwordx4 v211, v[108:111], s[74:75] offset:64
	v_fmac_f32_e32 v235, v108, v108
	v_fmac_f32_e32 v235, v109, v109
	v_fmac_f32_e32 v235, v110, v110
	v_fmac_f32_e32 v235, v111, v111
	v_pk_mul_f32 v[8:9], v[152:153], v[108:109]
	v_pk_mul_f32 v[10:11], v[154:155], v[110:111]
	v_cvt_pk_bf16_f32 v12, v12, v13
	v_cvt_pk_bf16_f32 v13, v14, v15
	v_cvt_pk_bf16_f32 v14, v8, v9
	v_cvt_pk_bf16_f32 v15, v10, v11
	s_nop 1
	v_permlane16_swap_b32 v12, v14
	v_permlane16_swap_b32 v13, v15
	global_store_dwordx4 v212, v[12:15], s[76:77] offset:0
	v_pk_fma_f32 v[104:105], v[4:5], v[68:69], v[104:105]
	v_pk_fma_f32 v[106:107], v[6:7], v[70:71], v[106:107]
	global_store_dwordx4 v211, v[104:107], s[74:75] offset:512
	v_fmac_f32_e32 v235, v104, v104
	v_fmac_f32_e32 v235, v105, v105
	v_fmac_f32_e32 v235, v106, v106
	v_fmac_f32_e32 v235, v107, v107
	v_pk_mul_f32 v[4:5], v[156:157], v[104:105]
	v_pk_mul_f32 v[6:7], v[158:159], v[106:107]
	v_pk_fma_f32 v[100:101], v[0:1], v[72:73], v[100:101]
	v_pk_fma_f32 v[102:103], v[2:3], v[74:75], v[102:103]
	global_store_dwordx4 v211, v[100:103], s[74:75] offset:576
	v_fmac_f32_e32 v235, v100, v100
	v_fmac_f32_e32 v235, v101, v101
	v_fmac_f32_e32 v235, v102, v102
	v_fmac_f32_e32 v235, v103, v103
	v_pk_mul_f32 v[0:1], v[160:161], v[100:101]
	v_pk_mul_f32 v[2:3], v[162:163], v[102:103]
	v_cvt_pk_bf16_f32 v4, v4, v5
	v_cvt_pk_bf16_f32 v5, v6, v7
	v_cvt_pk_bf16_f32 v6, v0, v1
	v_cvt_pk_bf16_f32 v7, v2, v3
	s_nop 1
	v_permlane16_swap_b32 v4, v6
	v_permlane16_swap_b32 v5, v7
	global_store_dwordx4 v212, v[4:7], s[76:77] offset:256
	ds_bpermute_b32 v164, v214, v216
	ds_bpermute_b32 v165, v214, v217
	ds_bpermute_b32 v166, v214, v218
	ds_bpermute_b32 v167, v214, v219
	ds_bpermute_b32 v168, v214, v228
	ds_bpermute_b32 v169, v214, v229
	ds_bpermute_b32 v170, v214, v234
	ds_bpermute_b32 v171, v214, v235
	s_waitcnt lgkmcnt(0)
	v_add_f32_e32 v216, v216, v164
	v_add_f32_e32 v217, v217, v165
	v_add_f32_e32 v218, v218, v166
	v_add_f32_e32 v219, v219, v167
	v_add_f32_e32 v228, v228, v168
	v_add_f32_e32 v229, v229, v169
	v_add_f32_e32 v234, v234, v170
	v_add_f32_e32 v235, v235, v171
	ds_bpermute_b32 v164, v215, v216
	ds_bpermute_b32 v165, v215, v217
	ds_bpermute_b32 v166, v215, v218
	ds_bpermute_b32 v167, v215, v219
	ds_bpermute_b32 v168, v215, v228
	ds_bpermute_b32 v169, v215, v229
	ds_bpermute_b32 v170, v215, v234
	ds_bpermute_b32 v171, v215, v235
	s_waitcnt lgkmcnt(0)
	v_add_f32_e32 v216, v216, v164
	v_add_f32_e32 v217, v217, v165
	v_add_f32_e32 v218, v218, v166
	v_add_f32_e32 v219, v219, v167
	v_add_f32_e32 v228, v228, v168
	v_add_f32_e32 v229, v229, v169
	v_add_f32_e32 v234, v234, v170
	v_add_f32_e32 v235, v235, v171
	s_and_saveexec_b64 s[44:45], s[40:41]
	s_cbranch_execz .Lresid_noatom
	global_atomic_add_f32 v213, v216, s[6:7] offset:0
	global_atomic_add_f32 v213, v217, s[6:7] offset:64
	global_atomic_add_f32 v213, v218, s[6:7] offset:128
	global_atomic_add_f32 v213, v219, s[6:7] offset:192
	global_atomic_add_f32 v213, v228, s[6:7] offset:512
	global_atomic_add_f32 v213, v229, s[6:7] offset:576
	global_atomic_add_f32 v213, v234, s[6:7] offset:640
	global_atomic_add_f32 v213, v235, s[6:7] offset:704
.Lresid_noatom:
	s_or_b64 exec, exec, s[44:45]
	s_branch .Lresid_done

.LBB0_966:
	s_or_b64 exec, exec, s[44:45]
.Lresid_done:
	s_andn2_b64 vcc, exec, s[42:43]
	s_mov_b64 s[42:43], -1
	s_cbranch_vccnz .LBB0_863
.LBB0_967:
	v_readlane_b32 s20, v255, 41
	v_readlane_b32 s21, v255, 42
	s_andn2_b64 vcc, exec, s[20:21]
	s_cbranch_vccnz .LBB0_862
	s_barrier
	s_branch .LBB0_862
